# merge phase: gate loads of a branch issued before that branch's K loop (independent of it); epilogue only converts and accumulates
# speedup vs baseline: 1.0001x; 1.0001x over previous
; DI float bf2f(bf16_t b) { return __uint_as_float(((unsigned)b) << 16); }
; DI void merge_phase(const Params& p, int l, char* smem) {
;     ...
;       const bf16_t* A = (br == 0 ? p.qa : br == 1 ? p.o_r : p.qm) + (size_t)mt * 128 * 512;
;       gemm_kloop64(A, 512, p.Wbr + ((size_t)(l * 3 + br) * DM + nt * 64) * 512, 512, 512, sm, acc);
; #pragma unroll
;       for (int i = 0; i < 2; i++)
; #pragma unroll
;         for (int r = 0; r < 4; r++) {
;           const int tok = mt * 128 + wave * 32 + i * 16 + g4 * 4 + r;
; #pragma unroll
;           for (int jn = 0; jn < 4; jn++) {
;             const int n = nt * 64 + jn * 16 + cl;
;             const float g = bf2f(p.G[(size_t)tok * 3072 + br * 1024 + n]);
.LBB0_1719:
	s_load_dwordx2 s[10:11], s[10:11], 0x0
	s_load_dwordx2 s[98:99], s[0:1], 0x160
	v_mov_b32_e32 v90, v182
	v_mov_b32_e32 v5, v164
	v_lshlrev_b32_e32 v4, 3, v90
	v_ashrrev_i32_e32 v69, 3, v90
	v_and_b32_e32 v91, 56, v4
	s_waitcnt lgkmcnt(0)
	s_add_u32 s10, s10, s4
	v_lshl_or_b32 v4, v69, 9, v91
	s_addc_u32 s11, s11, s5
	v_lshl_add_u64 v[252:253], s[98:99], 0, v[86:87]
	v_lshl_add_u64 v[252:253], v[252:253], 0, s[8:9]
	global_load_ushort v220, v[252:253], off
	global_load_ushort v222, v[252:253], off offset:32
	global_load_ushort v224, v[252:253], off offset:64
	global_load_ushort v226, v[252:253], off offset:96
	v_add_co_u32_e32 v252, vcc, s94, v252
	s_nop 1
	v_addc_co_u32_e32 v253, vcc, 0, v253, vcc
	global_load_ushort v221, v[252:253], off offset:2048
	global_load_ushort v223, v[252:253], off offset:2080
	global_load_ushort v225, v[252:253], off offset:2112
	global_load_ushort v227, v[252:253], off offset:2144
	v_lshl_add_u64 v[252:253], s[98:99], 0, v[86:87]
	v_lshl_add_u64 v[252:253], v[252:253], 0, s[8:9]
	v_add_co_u32_e32 v252, vcc, s70, v252
	s_nop 1
	v_addc_co_u32_e32 v253, vcc, 0, v253, vcc
	global_load_ushort v228, v[252:253], off
	global_load_ushort v230, v[252:253], off offset:32
	global_load_ushort v232, v[252:253], off offset:64
	global_load_ushort v234, v[252:253], off offset:96
	v_lshl_add_u64 v[252:253], s[98:99], 0, v[86:87]
	v_lshl_add_u64 v[252:253], v[252:253], 0, s[8:9]
	v_add_co_u32_e32 v252, vcc, s56, v252
	s_nop 1
	v_addc_co_u32_e32 v253, vcc, 0, v253, vcc
	global_load_ushort v229, v[252:253], off offset:2048
	global_load_ushort v231, v[252:253], off offset:2080
	global_load_ushort v233, v[252:253], off offset:2112
	global_load_ushort v235, v[252:253], off offset:2144
	v_lshl_add_u64 v[252:253], s[98:99], 0, v[88:89]
	v_lshl_add_u64 v[252:253], v[252:253], 0, s[8:9]
	global_load_ushort v236, v[252:253], off
	global_load_ushort v238, v[252:253], off offset:32
	global_load_ushort v240, v[252:253], off offset:64
	global_load_ushort v242, v[252:253], off offset:96
	v_add_co_u32_e32 v252, vcc, s94, v252
	s_nop 1
	v_addc_co_u32_e32 v253, vcc, 0, v253, vcc
	global_load_ushort v237, v[252:253], off offset:2048
	global_load_ushort v239, v[252:253], off offset:2080
	global_load_ushort v241, v[252:253], off offset:2112
	global_load_ushort v243, v[252:253], off offset:2144
	v_lshl_add_u64 v[252:253], s[98:99], 0, v[88:89]
	v_lshl_add_u64 v[252:253], v[252:253], 0, s[8:9]
	v_add_co_u32_e32 v252, vcc, s70, v252
	s_nop 1
	v_addc_co_u32_e32 v253, vcc, 0, v253, vcc
	global_load_ushort v244, v[252:253], off
	global_load_ushort v246, v[252:253], off offset:32
	global_load_ushort v248, v[252:253], off offset:64
	global_load_ushort v250, v[252:253], off offset:96
	v_lshl_add_u64 v[252:253], s[98:99], 0, v[88:89]
	v_lshl_add_u64 v[252:253], v[252:253], 0, s[8:9]
	v_add_co_u32_e32 v252, vcc, s56, v252
	s_nop 1
	v_addc_co_u32_e32 v253, vcc, 0, v253, vcc
	global_load_ushort v245, v[252:253], off offset:2048
	global_load_ushort v247, v[252:253], off offset:2080
	global_load_ushort v249, v[252:253], off offset:2112
	global_load_ushort v251, v[252:253], off offset:2144
	v_lshlrev_b64 v[20:21], 1, v[4:5]
	v_lshl_add_u64 v[92:93], s[10:11], 0, v[20:21]
	v_add_co_u32_e32 v94, vcc, s84, v92
	s_nop 1
	v_addc_co_u32_e32 v95, vcc, 0, v93, vcc
	v_add_co_u32_e32 v96, vcc, s85, v92
	s_barrier
	global_load_dwordx4 v[4:7], v[92:93], off
	global_load_dwordx4 v[8:11], v[94:95], off
	v_addc_co_u32_e32 v97, vcc, 0, v93, vcc
	v_add_co_u32_e32 v98, vcc, s55, v92
	global_load_dwordx4 v[12:15], v[96:97], off
	s_nop 0
	v_addc_co_u32_e32 v99, vcc, 0, v93, vcc
	global_load_dwordx4 v[16:19], v[98:99], off
	v_lshl_add_u64 v[100:101], s[6:7], 0, v[20:21]
	global_load_dwordx4 v[20:23], v[100:101], off
	v_add_co_u32_e32 v102, vcc, s84, v100
	v_mul_lo_u32 v69, v69, s54
	s_nop 0
	v_addc_co_u32_e32 v103, vcc, 0, v101, vcc
	global_load_dwordx4 v[24:27], v[102:103], off
	global_load_dwordx4 v[48:51], v[92:93], off offset:128
	global_load_dwordx4 v[44:47], v[94:95], off offset:128
	global_load_dwordx4 v[40:43], v[96:97], off offset:128
	global_load_dwordx4 v[36:39], v[98:99], off offset:128
	global_load_dwordx4 v[32:35], v[100:101], off offset:128
	global_load_dwordx4 v[28:31], v[102:103], off offset:128
	v_and_b32_e32 v107, 15, v90
	v_lshrrev_b32_e32 v108, 1, v90
	v_lshl_add_u32 v69, v91, 1, v69
	s_mov_b32 s10, 0xfffffe0
	s_add_i32 s15, s15, 1
	s_waitcnt vmcnt(11)
	ds_write_b128 v69, v[4:7]
	s_waitcnt vmcnt(10)
	ds_write_b128 v69, v[8:11] offset:4608
	s_waitcnt vmcnt(9)
	ds_write_b128 v69, v[12:15] offset:9216
	s_waitcnt vmcnt(8)
	ds_write_b128 v69, v[16:19] offset:13824
	s_waitcnt vmcnt(7)
	ds_write_b128 v69, v[20:23] offset:18432
	s_waitcnt vmcnt(6)
	ds_write_b128 v69, v[24:27] offset:23040
	v_and_or_b32 v5, v108, s10, v107
	v_and_b32_e32 v4, 48, v90
	v_mad_u64_u32 v[90:91], s[10:11], v5, s54, v[4:5]
	v_mul_u32_u24_e32 v5, 0x48, v107
	s_waitcnt lgkmcnt(0)
	s_barrier
; DI void gemm_kloop64(const bf16_t* __restrict__ A, int lda, const bf16_t* __restrict__ B, int ldb, int K, bf16_t* sm,
;                      f32x4 (&acc)[2][4]) {
;     ...
;   __syncthreads();
;   GLOAD(ra0, rb0, 0)
;   GLOAD(ra1, rb1, 64)
;   SSTORE(ra0, rb0, 0)
;   __syncthreads();
;   for (int kt = 0; kt < nk - 2; kt += 2) {
;     GLOAD(ra0, rb0, (kt + 2) << 6)
;     COMPUTE(0)
;     SSTORE(ra1, rb1, 1)
;     __syncthreads();
;     GLOAD(ra1, rb1, (kt + 3) << 6)
;     COMPUTE(1)
;     SSTORE(ra0, rb0, 0)
;     __syncthreads();
	v_lshl_add_u32 v91, v5, 1, v4
	global_load_dwordx4 v[4:7], v[92:93], off offset:256
	global_load_dwordx4 v[8:11], v[94:95], off offset:256
	global_load_dwordx4 v[12:15], v[96:97], off offset:256
	global_load_dwordx4 v[16:19], v[98:99], off offset:256
	global_load_dwordx4 v[20:23], v[100:101], off offset:256
	global_load_dwordx4 v[24:27], v[102:103], off offset:256
	ds_read_b128 v[108:111], v90
	ds_read_b128 v[112:115], v90 offset:2304
	ds_read_b128 v[116:119], v91 offset:18432
	ds_read_b128 v[120:123], v91 offset:20736
	ds_read_b128 v[124:127], v91 offset:23040
	ds_read_b128 v[128:131], v91 offset:25344
	s_waitcnt lgkmcnt(3)
	v_mfma_f32_16x16x32_bf16 v[132:135], v[108:111], v[116:119], 0
	s_waitcnt lgkmcnt(2)
	v_mfma_f32_16x16x32_bf16 v[136:139], v[108:111], v[120:123], 0
	s_waitcnt lgkmcnt(1)
	v_mfma_f32_16x16x32_bf16 v[140:143], v[108:111], v[124:127], 0
	s_waitcnt lgkmcnt(0)
	v_mfma_f32_16x16x32_bf16 v[108:111], v[108:111], v[128:131], 0
	v_mfma_f32_16x16x32_bf16 v[116:119], v[112:115], v[116:119], 0
	v_mfma_f32_16x16x32_bf16 v[120:123], v[112:115], v[120:123], 0
	v_mfma_f32_16x16x32_bf16 v[124:127], v[112:115], v[124:127], 0
	v_mfma_f32_16x16x32_bf16 v[112:115], v[112:115], v[128:131], 0
	ds_read_b128 v[128:131], v90 offset:64
	ds_read_b128 v[144:147], v90 offset:2368
	ds_read_b128 v[148:151], v91 offset:18496
	ds_read_b128 v[152:155], v91 offset:20800
	ds_read_b128 v[156:159], v91 offset:23104
	ds_read_b128 v[160:163], v91 offset:25408
	s_waitcnt vmcnt(11)
	ds_write_b128 v69, v[48:51] offset:36864
	s_waitcnt vmcnt(10)
	ds_write_b128 v69, v[44:47] offset:41472
	s_waitcnt vmcnt(9)
	ds_write_b128 v69, v[40:43] offset:46080
	s_waitcnt vmcnt(8)
	ds_write_b128 v69, v[36:39] offset:50688
	s_waitcnt vmcnt(7)
	ds_write_b128 v69, v[32:35] offset:55296
	s_waitcnt vmcnt(6)
	ds_write_b128 v69, v[28:31] offset:59904
	s_waitcnt lgkmcnt(0)
	s_barrier
	global_load_dwordx4 v[28:31], v[92:93], off offset:384
	global_load_dwordx4 v[32:35], v[94:95], off offset:384
	global_load_dwordx4 v[36:39], v[96:97], off offset:384
	global_load_dwordx4 v[40:43], v[98:99], off offset:384
	global_load_dwordx4 v[44:47], v[100:101], off offset:384
	global_load_dwordx4 v[48:51], v[102:103], off offset:384
	v_mfma_f32_16x16x32_bf16 v[132:135], v[128:131], v[148:151], v[132:135]
	v_mfma_f32_16x16x32_bf16 v[136:139], v[128:131], v[152:155], v[136:139]
	v_mfma_f32_16x16x32_bf16 v[140:143], v[128:131], v[156:159], v[140:143]
	v_mfma_f32_16x16x32_bf16 v[108:111], v[128:131], v[160:163], v[108:111]
	v_mfma_f32_16x16x32_bf16 v[116:119], v[144:147], v[148:151], v[116:119]
	v_mfma_f32_16x16x32_bf16 v[120:123], v[144:147], v[152:155], v[120:123]
	v_mfma_f32_16x16x32_bf16 v[124:127], v[144:147], v[156:159], v[124:127]
	v_mfma_f32_16x16x32_bf16 v[112:115], v[144:147], v[160:163], v[112:115]
	ds_read_b128 v[128:131], v90 offset:36864
	ds_read_b128 v[144:147], v90 offset:39168
	ds_read_b128 v[148:151], v91 offset:55296
	ds_read_b128 v[152:155], v91 offset:57600
	ds_read_b128 v[156:159], v91 offset:59904
	ds_read_b128 v[160:163], v91 offset:62208
	s_waitcnt lgkmcnt(3)
	v_mfma_f32_16x16x32_bf16 v[132:135], v[128:131], v[148:151], v[132:135]
	s_waitcnt lgkmcnt(2)
	v_mfma_f32_16x16x32_bf16 v[136:139], v[128:131], v[152:155], v[136:139]
	s_waitcnt lgkmcnt(1)
	v_mfma_f32_16x16x32_bf16 v[140:143], v[128:131], v[156:159], v[140:143]
	s_waitcnt lgkmcnt(0)
	v_mfma_f32_16x16x32_bf16 v[108:111], v[128:131], v[160:163], v[108:111]
	v_mfma_f32_16x16x32_bf16 v[116:119], v[144:147], v[148:151], v[116:119]
	v_mfma_f32_16x16x32_bf16 v[120:123], v[144:147], v[152:155], v[120:123]
	v_mfma_f32_16x16x32_bf16 v[124:127], v[144:147], v[156:159], v[124:127]
	v_mfma_f32_16x16x32_bf16 v[112:115], v[144:147], v[160:163], v[112:115]
	ds_read_b128 v[128:131], v90 offset:36928
	ds_read_b128 v[144:147], v90 offset:39232
	ds_read_b128 v[148:151], v91 offset:55360
	ds_read_b128 v[152:155], v91 offset:57664
	ds_read_b128 v[156:159], v91 offset:59968
	ds_read_b128 v[160:163], v91 offset:62272
	s_waitcnt vmcnt(11)
	ds_write_b128 v69, v[4:7]
	s_waitcnt vmcnt(10)
	ds_write_b128 v69, v[8:11] offset:4608
	s_waitcnt vmcnt(9)
	ds_write_b128 v69, v[12:15] offset:9216
	s_waitcnt vmcnt(8)
	ds_write_b128 v69, v[16:19] offset:13824
	s_waitcnt vmcnt(7)
	ds_write_b128 v69, v[20:23] offset:18432
	s_waitcnt vmcnt(6)
	ds_write_b128 v69, v[24:27] offset:23040
	s_waitcnt lgkmcnt(0)
	s_barrier
	global_load_dwordx4 v[4:7], v[92:93], off offset:512
	global_load_dwordx4 v[8:11], v[94:95], off offset:512
	global_load_dwordx4 v[12:15], v[96:97], off offset:512
	global_load_dwordx4 v[16:19], v[98:99], off offset:512
	global_load_dwordx4 v[20:23], v[100:101], off offset:512
	global_load_dwordx4 v[24:27], v[102:103], off offset:512
	v_mfma_f32_16x16x32_bf16 v[132:135], v[128:131], v[148:151], v[132:135]
	v_mfma_f32_16x16x32_bf16 v[136:139], v[128:131], v[152:155], v[136:139]
	v_mfma_f32_16x16x32_bf16 v[140:143], v[128:131], v[156:159], v[140:143]
	v_mfma_f32_16x16x32_bf16 v[108:111], v[128:131], v[160:163], v[108:111]
	v_mfma_f32_16x16x32_bf16 v[116:119], v[144:147], v[148:151], v[116:119]
	v_mfma_f32_16x16x32_bf16 v[120:123], v[144:147], v[152:155], v[120:123]
	v_mfma_f32_16x16x32_bf16 v[124:127], v[144:147], v[156:159], v[124:127]
	v_mfma_f32_16x16x32_bf16 v[112:115], v[144:147], v[160:163], v[112:115]
	ds_read_b128 v[128:131], v90
	ds_read_b128 v[144:147], v90 offset:2304
	ds_read_b128 v[148:151], v91 offset:18432
	ds_read_b128 v[152:155], v91 offset:20736
	ds_read_b128 v[156:159], v91 offset:23040
	ds_read_b128 v[160:163], v91 offset:25344
	s_waitcnt lgkmcnt(3)
	v_mfma_f32_16x16x32_bf16 v[132:135], v[128:131], v[148:151], v[132:135]
	s_waitcnt lgkmcnt(2)
	v_mfma_f32_16x16x32_bf16 v[136:139], v[128:131], v[152:155], v[136:139]
	s_waitcnt lgkmcnt(1)
	v_mfma_f32_16x16x32_bf16 v[140:143], v[128:131], v[156:159], v[140:143]
	s_waitcnt lgkmcnt(0)
	v_mfma_f32_16x16x32_bf16 v[108:111], v[128:131], v[160:163], v[108:111]
	v_mfma_f32_16x16x32_bf16 v[116:119], v[144:147], v[148:151], v[116:119]
	v_mfma_f32_16x16x32_bf16 v[120:123], v[144:147], v[152:155], v[120:123]
	v_mfma_f32_16x16x32_bf16 v[124:127], v[144:147], v[156:159], v[124:127]
	v_mfma_f32_16x16x32_bf16 v[112:115], v[144:147], v[160:163], v[112:115]
	ds_read_b128 v[128:131], v90 offset:64
	ds_read_b128 v[144:147], v90 offset:2368
	ds_read_b128 v[148:151], v91 offset:18496
	ds_read_b128 v[152:155], v91 offset:20800
	ds_read_b128 v[156:159], v91 offset:23104
	ds_read_b128 v[160:163], v91 offset:25408
	s_waitcnt vmcnt(11)
	ds_write_b128 v69, v[28:31] offset:36864
	s_waitcnt vmcnt(10)
	ds_write_b128 v69, v[32:35] offset:41472
	s_waitcnt vmcnt(9)
	ds_write_b128 v69, v[36:39] offset:46080
	s_waitcnt vmcnt(8)
	ds_write_b128 v69, v[40:43] offset:50688
	s_waitcnt vmcnt(7)
	ds_write_b128 v69, v[44:47] offset:55296
	s_waitcnt vmcnt(6)
	ds_write_b128 v69, v[48:51] offset:59904
	s_waitcnt lgkmcnt(0)
	s_barrier
; DI void gemm_kloop64(const bf16_t* __restrict__ A, int lda, const bf16_t* __restrict__ B, int ldb, int K, bf16_t* sm,
;                      f32x4 (&acc)[2][4]) {
;     ...
;   for (int kt = 0; kt < nk - 2; kt += 2) {
;     GLOAD(ra0, rb0, (kt + 2) << 6)
;     COMPUTE(0)
;     SSTORE(ra1, rb1, 1)
;     __syncthreads();
;     GLOAD(ra1, rb1, (kt + 3) << 6)
;     COMPUTE(1)
;     SSTORE(ra0, rb0, 0)
;     __syncthreads();
;   }
	global_load_dwordx4 v[44:47], v[92:93], off offset:640
	global_load_dwordx4 v[48:51], v[94:95], off offset:640
	global_load_dwordx4 v[40:43], v[96:97], off offset:640
	global_load_dwordx4 v[32:35], v[98:99], off offset:640
	global_load_dwordx4 v[36:39], v[100:101], off offset:640
	global_load_dwordx4 v[28:31], v[102:103], off offset:640
	v_mfma_f32_16x16x32_bf16 v[132:135], v[128:131], v[148:151], v[132:135]
	v_mfma_f32_16x16x32_bf16 v[136:139], v[128:131], v[152:155], v[136:139]
	v_mfma_f32_16x16x32_bf16 v[140:143], v[128:131], v[156:159], v[140:143]
	v_mfma_f32_16x16x32_bf16 v[108:111], v[128:131], v[160:163], v[108:111]
	v_mfma_f32_16x16x32_bf16 v[116:119], v[144:147], v[148:151], v[116:119]
	v_mfma_f32_16x16x32_bf16 v[120:123], v[144:147], v[152:155], v[120:123]
	v_mfma_f32_16x16x32_bf16 v[124:127], v[144:147], v[156:159], v[124:127]
	v_mfma_f32_16x16x32_bf16 v[112:115], v[144:147], v[160:163], v[112:115]
	ds_read_b128 v[128:131], v90 offset:36864
	ds_read_b128 v[144:147], v90 offset:39168
	ds_read_b128 v[148:151], v91 offset:55296
	ds_read_b128 v[152:155], v91 offset:57600
	ds_read_b128 v[156:159], v91 offset:59904
	ds_read_b128 v[160:163], v91 offset:62208
	s_waitcnt lgkmcnt(3)
	v_mfma_f32_16x16x32_bf16 v[132:135], v[128:131], v[148:151], v[132:135]
	s_waitcnt lgkmcnt(2)
	v_mfma_f32_16x16x32_bf16 v[136:139], v[128:131], v[152:155], v[136:139]
	s_waitcnt lgkmcnt(1)
	v_mfma_f32_16x16x32_bf16 v[140:143], v[128:131], v[156:159], v[140:143]
	s_waitcnt lgkmcnt(0)
	v_mfma_f32_16x16x32_bf16 v[108:111], v[128:131], v[160:163], v[108:111]
	v_mfma_f32_16x16x32_bf16 v[116:119], v[144:147], v[148:151], v[116:119]
	v_mfma_f32_16x16x32_bf16 v[120:123], v[144:147], v[152:155], v[120:123]
	v_mfma_f32_16x16x32_bf16 v[124:127], v[144:147], v[156:159], v[124:127]
	v_mfma_f32_16x16x32_bf16 v[112:115], v[144:147], v[160:163], v[112:115]
	ds_read_b128 v[128:131], v90 offset:36928
	ds_read_b128 v[144:147], v90 offset:39232
	ds_read_b128 v[148:151], v91 offset:55360
	ds_read_b128 v[152:155], v91 offset:57664
	ds_read_b128 v[156:159], v91 offset:59968
	ds_read_b128 v[160:163], v91 offset:62272
	s_waitcnt vmcnt(11)
	ds_write_b128 v69, v[4:7]
	s_waitcnt vmcnt(10)
	ds_write_b128 v69, v[8:11] offset:4608
	s_waitcnt vmcnt(9)
	ds_write_b128 v69, v[12:15] offset:9216
	s_waitcnt vmcnt(8)
	ds_write_b128 v69, v[16:19] offset:13824
	s_waitcnt vmcnt(7)
	ds_write_b128 v69, v[20:23] offset:18432
	s_waitcnt vmcnt(6)
	ds_write_b128 v69, v[24:27] offset:23040
	s_waitcnt lgkmcnt(0)
	s_barrier
	global_load_dwordx4 v[16:19], v[92:93], off offset:768
	global_load_dwordx4 v[20:23], v[94:95], off offset:768
	global_load_dwordx4 v[24:27], v[96:97], off offset:768
	global_load_dwordx4 v[4:7], v[98:99], off offset:768
	global_load_dwordx4 v[8:11], v[100:101], off offset:768
	global_load_dwordx4 v[12:15], v[102:103], off offset:768
	v_mfma_f32_16x16x32_bf16 v[132:135], v[128:131], v[148:151], v[132:135]
	v_mfma_f32_16x16x32_bf16 v[136:139], v[128:131], v[152:155], v[136:139]
	v_mfma_f32_16x16x32_bf16 v[140:143], v[128:131], v[156:159], v[140:143]
	v_mfma_f32_16x16x32_bf16 v[108:111], v[128:131], v[160:163], v[108:111]
	v_mfma_f32_16x16x32_bf16 v[116:119], v[144:147], v[148:151], v[116:119]
	v_mfma_f32_16x16x32_bf16 v[120:123], v[144:147], v[152:155], v[120:123]
	v_mfma_f32_16x16x32_bf16 v[124:127], v[144:147], v[156:159], v[124:127]
	v_mfma_f32_16x16x32_bf16 v[112:115], v[144:147], v[160:163], v[112:115]
	ds_read_b128 v[128:131], v90
	ds_read_b128 v[144:147], v90 offset:2304
	ds_read_b128 v[148:151], v91 offset:18432
	ds_read_b128 v[152:155], v91 offset:20736
	ds_read_b128 v[156:159], v91 offset:23040
	ds_read_b128 v[160:163], v91 offset:25344
	s_waitcnt lgkmcnt(3)
	v_mfma_f32_16x16x32_bf16 v[132:135], v[128:131], v[148:151], v[132:135]
	s_waitcnt lgkmcnt(2)
	v_mfma_f32_16x16x32_bf16 v[136:139], v[128:131], v[152:155], v[136:139]
	s_waitcnt lgkmcnt(1)
	v_mfma_f32_16x16x32_bf16 v[140:143], v[128:131], v[156:159], v[140:143]
	s_waitcnt lgkmcnt(0)
	v_mfma_f32_16x16x32_bf16 v[108:111], v[128:131], v[160:163], v[108:111]
	v_mfma_f32_16x16x32_bf16 v[116:119], v[144:147], v[148:151], v[116:119]
	v_mfma_f32_16x16x32_bf16 v[120:123], v[144:147], v[152:155], v[120:123]
	v_mfma_f32_16x16x32_bf16 v[124:127], v[144:147], v[156:159], v[124:127]
	v_mfma_f32_16x16x32_bf16 v[112:115], v[144:147], v[160:163], v[112:115]
	ds_read_b128 v[128:131], v90 offset:64
	ds_read_b128 v[144:147], v90 offset:2368
	ds_read_b128 v[148:151], v91 offset:18496
	ds_read_b128 v[152:155], v91 offset:20800
	ds_read_b128 v[156:159], v91 offset:23104
	ds_read_b128 v[160:163], v91 offset:25408
	s_waitcnt vmcnt(11)
	ds_write_b128 v69, v[44:47] offset:36864
	s_waitcnt vmcnt(10)
	ds_write_b128 v69, v[48:51] offset:41472
	s_waitcnt vmcnt(9)
	ds_write_b128 v69, v[40:43] offset:46080
	s_waitcnt vmcnt(8)
	ds_write_b128 v69, v[32:35] offset:50688
	s_waitcnt vmcnt(7)
	ds_write_b128 v69, v[36:39] offset:55296
	s_waitcnt vmcnt(6)
	ds_write_b128 v69, v[28:31] offset:59904
	s_waitcnt lgkmcnt(0)
	s_barrier
; DI void gemm_kloop64(const bf16_t* __restrict__ A, int lda, const bf16_t* __restrict__ B, int ldb, int K, bf16_t* sm,
;                      f32x4 (&acc)[2][4]) {
;     ...
;   COMPUTE(0)
;   SSTORE(ra1, rb1, 1)
;   __syncthreads();
;   COMPUTE(1)
;   __syncthreads();
	global_load_dwordx4 v[40:43], v[92:93], off offset:896
	global_load_dwordx4 v[44:47], v[94:95], off offset:896
	global_load_dwordx4 v[48:51], v[96:97], off offset:896
	global_load_dwordx4 v[28:31], v[98:99], off offset:896
	global_load_dwordx4 v[32:35], v[100:101], off offset:896
	global_load_dwordx4 v[36:39], v[102:103], off offset:896
	v_mfma_f32_16x16x32_bf16 v[132:135], v[128:131], v[148:151], v[132:135]
	v_mfma_f32_16x16x32_bf16 v[136:139], v[128:131], v[152:155], v[136:139]
	v_mfma_f32_16x16x32_bf16 v[140:143], v[128:131], v[156:159], v[140:143]
	v_mfma_f32_16x16x32_bf16 v[108:111], v[128:131], v[160:163], v[108:111]
	v_mfma_f32_16x16x32_bf16 v[116:119], v[144:147], v[148:151], v[116:119]
	v_mfma_f32_16x16x32_bf16 v[120:123], v[144:147], v[152:155], v[120:123]
	v_mfma_f32_16x16x32_bf16 v[124:127], v[144:147], v[156:159], v[124:127]
	v_mfma_f32_16x16x32_bf16 v[112:115], v[144:147], v[160:163], v[112:115]
	ds_read_b128 v[92:95], v90 offset:36864
	ds_read_b128 v[96:99], v90 offset:39168
	ds_read_b128 v[100:103], v91 offset:55296
	ds_read_b128 v[128:131], v91 offset:57600
	ds_read_b128 v[144:147], v91 offset:59904
	ds_read_b128 v[148:151], v91 offset:62208
	s_waitcnt lgkmcnt(3)
	v_mfma_f32_16x16x32_bf16 v[132:135], v[92:95], v[100:103], v[132:135]
	s_waitcnt lgkmcnt(2)
	v_mfma_f32_16x16x32_bf16 v[136:139], v[92:95], v[128:131], v[136:139]
	s_waitcnt lgkmcnt(1)
	v_mfma_f32_16x16x32_bf16 v[140:143], v[92:95], v[144:147], v[140:143]
	s_waitcnt lgkmcnt(0)
	v_mfma_f32_16x16x32_bf16 v[92:95], v[92:95], v[148:151], v[108:111]
	v_mfma_f32_16x16x32_bf16 v[100:103], v[96:99], v[100:103], v[116:119]
	v_mfma_f32_16x16x32_bf16 v[108:111], v[96:99], v[128:131], v[120:123]
	v_mfma_f32_16x16x32_bf16 v[116:119], v[96:99], v[144:147], v[124:127]
	v_mfma_f32_16x16x32_bf16 v[96:99], v[96:99], v[148:151], v[112:115]
	s_nop 2
	ds_read_b128 v[112:115], v90 offset:36928
	ds_read_b128 v[120:123], v90 offset:39232
	ds_read_b128 v[124:127], v91 offset:55360
	ds_read_b128 v[128:131], v91 offset:57664
	ds_read_b128 v[144:147], v91 offset:59968
	ds_read_b128 v[148:151], v91 offset:62272
	s_waitcnt vmcnt(11)
	ds_write_b128 v69, v[16:19]
	s_waitcnt vmcnt(10)
	ds_write_b128 v69, v[20:23] offset:4608
	s_waitcnt vmcnt(9)
	ds_write_b128 v69, v[24:27] offset:9216
	s_waitcnt vmcnt(8)
	ds_write_b128 v69, v[4:7] offset:13824
	s_waitcnt vmcnt(7)
	ds_write_b128 v69, v[8:11] offset:18432
	s_waitcnt vmcnt(6)
	ds_write_b128 v69, v[12:15] offset:23040
	s_waitcnt lgkmcnt(0)
	s_barrier
	ds_read_b128 v[4:7], v90
	ds_read_b128 v[8:11], v90 offset:2304
	ds_read_b128 v[12:15], v91 offset:18432
	ds_read_b128 v[16:19], v91 offset:20736
	ds_read_b128 v[20:23], v91 offset:23040
	ds_read_b128 v[24:27], v91 offset:25344
	v_mfma_f32_16x16x32_bf16 v[132:135], v[112:115], v[124:127], v[132:135]
	v_mfma_f32_16x16x32_bf16 v[136:139], v[112:115], v[128:131], v[136:139]
	v_mfma_f32_16x16x32_bf16 v[140:143], v[112:115], v[144:147], v[140:143]
	v_mfma_f32_16x16x32_bf16 v[92:95], v[112:115], v[148:151], v[92:95]
	v_mfma_f32_16x16x32_bf16 v[100:103], v[120:123], v[124:127], v[100:103]
	v_mfma_f32_16x16x32_bf16 v[108:111], v[120:123], v[128:131], v[108:111]
	v_mfma_f32_16x16x32_bf16 v[112:115], v[120:123], v[144:147], v[116:119]
	v_mfma_f32_16x16x32_bf16 v[96:99], v[120:123], v[148:151], v[96:99]
	s_waitcnt lgkmcnt(3)
	v_mfma_f32_16x16x32_bf16 v[116:119], v[4:7], v[12:15], v[132:135]
	s_waitcnt lgkmcnt(2)
	v_mfma_f32_16x16x32_bf16 v[120:123], v[4:7], v[16:19], v[136:139]
	s_waitcnt lgkmcnt(1)
	v_mfma_f32_16x16x32_bf16 v[124:127], v[4:7], v[20:23], v[140:143]
	s_waitcnt lgkmcnt(0)
	v_mfma_f32_16x16x32_bf16 v[4:7], v[4:7], v[24:27], v[92:95]
	v_mfma_f32_16x16x32_bf16 v[12:15], v[8:11], v[12:15], v[100:103]
	v_mfma_f32_16x16x32_bf16 v[16:19], v[8:11], v[16:19], v[108:111]
	v_mfma_f32_16x16x32_bf16 v[20:23], v[8:11], v[20:23], v[112:115]
	v_mfma_f32_16x16x32_bf16 v[8:11], v[8:11], v[24:27], v[96:99]
	ds_read_b128 v[24:27], v90 offset:64
	ds_read_b128 v[92:95], v90 offset:2368
	s_nop 0
	ds_read_b128 v[96:99], v91 offset:18496
	ds_read_b128 v[100:103], v91 offset:20800
	ds_read_b128 v[108:111], v91 offset:23104
	ds_read_b128 v[112:115], v91 offset:25408
	s_waitcnt vmcnt(5)
	ds_write_b128 v69, v[40:43] offset:36864
	s_waitcnt vmcnt(4)
	ds_write_b128 v69, v[44:47] offset:41472
	s_waitcnt vmcnt(3)
	ds_write_b128 v69, v[48:51] offset:46080
	s_waitcnt vmcnt(2)
	ds_write_b128 v69, v[28:31] offset:50688
	s_waitcnt vmcnt(1)
	ds_write_b128 v69, v[32:35] offset:55296
	s_waitcnt vmcnt(0)
	ds_write_b128 v69, v[36:39] offset:59904
	s_waitcnt lgkmcnt(0)
	v_mfma_f32_16x16x32_bf16 v[116:119], v[24:27], v[96:99], v[116:119]
	s_barrier
; DI float bf2f(bf16_t b) { return __uint_as_float(((unsigned)b) << 16); }
; DI void gemm_kloop64(const bf16_t* __restrict__ A, int lda, const bf16_t* __restrict__ B, int ldb, int K, bf16_t* sm,
;                      f32x4 (&acc)[2][4]) {
;     ...
;   COMPUTE(0)
;   SSTORE(ra1, rb1, 1)
;   __syncthreads();
;   COMPUTE(1)
;   __syncthreads();
; DI void merge_phase(const Params& p, int l, char* smem) {
;     ...
; #pragma unroll
;       for (int i = 0; i < 2; i++)
; #pragma unroll
;         for (int r = 0; r < 4; r++) {
;           const int tok = mt * 128 + wave * 32 + i * 16 + g4 * 4 + r;
; #pragma unroll
;           for (int jn = 0; jn < 4; jn++) {
;             const int n = nt * 64 + jn * 16 + cl;
;             const float g = bf2f(p.G[(size_t)tok * 3072 + br * 1024 + n]);
;             tot[i][jn][r] += g * acc[i][jn][r];
;           }
;         }
;     }
	v_mfma_f32_16x16x32_bf16 v[120:123], v[24:27], v[100:103], v[120:123]
	v_mfma_f32_16x16x32_bf16 v[124:127], v[24:27], v[108:111], v[124:127]
	v_mfma_f32_16x16x32_bf16 v[4:7], v[24:27], v[112:115], v[4:7]
	ds_read_b128 v[24:27], v90 offset:36864
	ds_read_b128 v[28:31], v90 offset:39168
	ds_read_b128 v[32:35], v91 offset:55296
	ds_read_b128 v[36:39], v91 offset:57600
	ds_read_b128 v[40:43], v91 offset:59904
	ds_read_b128 v[44:47], v91 offset:62208
	v_mfma_f32_16x16x32_bf16 v[12:15], v[92:95], v[96:99], v[12:15]
	v_mfma_f32_16x16x32_bf16 v[16:19], v[92:95], v[100:103], v[16:19]
	v_mfma_f32_16x16x32_bf16 v[20:23], v[92:95], v[108:111], v[20:23]
	v_mfma_f32_16x16x32_bf16 v[8:11], v[92:95], v[112:115], v[8:11]
	s_waitcnt lgkmcnt(3)
	v_mfma_f32_16x16x32_bf16 v[48:51], v[24:27], v[32:35], v[116:119]
	s_waitcnt lgkmcnt(2)
	v_mfma_f32_16x16x32_bf16 v[92:95], v[24:27], v[36:39], v[120:123]
	s_waitcnt lgkmcnt(1)
	v_mfma_f32_16x16x32_bf16 v[96:99], v[24:27], v[40:43], v[124:127]
	s_waitcnt lgkmcnt(0)
	v_mfma_f32_16x16x32_bf16 v[4:7], v[24:27], v[44:47], v[4:7]
	v_mfma_f32_16x16x32_bf16 v[12:15], v[28:31], v[32:35], v[12:15]
	v_mfma_f32_16x16x32_bf16 v[24:27], v[28:31], v[36:39], v[16:19]
	v_mfma_f32_16x16x32_bf16 v[20:23], v[28:31], v[40:43], v[20:23]
	v_mfma_f32_16x16x32_bf16 v[28:31], v[28:31], v[44:47], v[8:11]
	s_nop 2
	ds_read_b128 v[8:11], v90 offset:36928
	ds_read_b128 v[32:35], v90 offset:39232
	ds_read_b128 v[16:19], v91 offset:55360
	ds_read_b128 v[36:39], v91 offset:57664
	ds_read_b128 v[40:43], v91 offset:59968
	ds_read_b128 v[44:47], v91 offset:62272
	s_waitcnt lgkmcnt(0)
	s_barrier
	v_mfma_f32_16x16x32_bf16 v[48:51], v[8:11], v[16:19], v[48:51]
	v_mfma_f32_16x16x32_bf16 v[90:93], v[8:11], v[36:39], v[92:95]
	v_mfma_f32_16x16x32_bf16 v[94:97], v[8:11], v[40:43], v[96:99]
	v_mfma_f32_16x16x32_bf16 v[98:101], v[8:11], v[44:47], v[4:7]
	v_mfma_f32_16x16x32_bf16 v[8:11], v[32:35], v[40:43], v[20:23]
	v_mfma_f32_16x16x32_bf16 v[16:19], v[32:35], v[16:19], v[12:15]
	v_mfma_f32_16x16x32_bf16 v[12:15], v[32:35], v[36:39], v[24:27]
	v_mfma_f32_16x16x32_bf16 v[4:7], v[32:35], v[44:47], v[28:31]
	s_waitcnt vmcnt(0)
	v_lshlrev_b32_e32 v220, 16, v220
	v_lshlrev_b32_e32 v221, 16, v221
	v_pk_fma_f32 v[84:85], v[48:49], v[220:221], v[84:85]
	v_lshlrev_b32_e32 v222, 16, v222
	v_lshlrev_b32_e32 v223, 16, v223
	v_pk_fma_f32 v[82:83], v[90:91], v[222:223], v[82:83]
	v_lshlrev_b32_e32 v224, 16, v224
	v_lshlrev_b32_e32 v225, 16, v225
	v_pk_fma_f32 v[80:81], v[94:95], v[224:225], v[80:81]
	v_lshlrev_b32_e32 v226, 16, v226
	v_lshlrev_b32_e32 v227, 16, v227
	v_pk_fma_f32 v[78:79], v[98:99], v[226:227], v[78:79]
	v_lshlrev_b32_e32 v236, 16, v236
	v_lshlrev_b32_e32 v237, 16, v237
	v_pk_fma_f32 v[66:67], v[16:17], v[236:237], v[66:67]
	v_lshlrev_b32_e32 v238, 16, v238
	v_lshlrev_b32_e32 v239, 16, v239
	v_pk_fma_f32 v[64:65], v[12:13], v[238:239], v[64:65]
	v_lshlrev_b32_e32 v240, 16, v240
	v_lshlrev_b32_e32 v241, 16, v241
	v_pk_fma_f32 v[62:63], v[8:9], v[240:241], v[62:63]
	v_lshlrev_b32_e32 v242, 16, v242
	v_lshlrev_b32_e32 v243, 16, v243
	v_pk_fma_f32 v[58:59], v[4:5], v[242:243], v[58:59]
	v_lshlrev_b32_e32 v228, 16, v228
	v_lshlrev_b32_e32 v229, 16, v229
	v_pk_fma_f32 v[76:77], v[50:51], v[228:229], v[76:77]
	v_lshlrev_b32_e32 v230, 16, v230
	v_lshlrev_b32_e32 v231, 16, v231
	v_pk_fma_f32 v[74:75], v[92:93], v[230:231], v[74:75]
	v_lshlrev_b32_e32 v232, 16, v232
	v_lshlrev_b32_e32 v233, 16, v233
	v_pk_fma_f32 v[72:73], v[96:97], v[232:233], v[72:73]
	v_lshlrev_b32_e32 v234, 16, v234
	v_lshlrev_b32_e32 v235, 16, v235
	v_pk_fma_f32 v[70:71], v[100:101], v[234:235], v[70:71]
	v_lshlrev_b32_e32 v244, 16, v244
	v_lshlrev_b32_e32 v245, 16, v245
	v_pk_fma_f32 v[60:61], v[18:19], v[244:245], v[60:61]
	v_lshlrev_b32_e32 v246, 16, v246
	v_lshlrev_b32_e32 v247, 16, v247
	v_pk_fma_f32 v[56:57], v[14:15], v[246:247], v[56:57]
	v_lshlrev_b32_e32 v248, 16, v248
	v_lshlrev_b32_e32 v249, 16, v249
	v_pk_fma_f32 v[54:55], v[10:11], v[248:249], v[54:55]
	v_lshlrev_b32_e32 v250, 16, v250
	v_lshlrev_b32_e32 v251, 16, v251
	v_pk_fma_f32 v[52:53], v[6:7], v[250:251], v[52:53]
	s_add_u32 s8, s8, 0x800
	s_addc_u32 s9, s9, 0
	s_add_u32 s6, s6, 0x100000
	s_addc_u32 s7, s7, 0
	s_cmpk_eq_i32 s8, 0x1800
	s_cbranch_scc1 .LBB0_1717
